# adaLN GEMV loop unrolled by two with all 16 row loads issued up front (twice the bytes in flight per wave)
# speedup vs baseline: 1.0034x; 1.0034x over previous
; #define LAS __attribute__((address_space(3)))
; __device__ __forceinline__ void p0_mod(LAS unsigned char* lds, const float* c, const float* w_ada, const float* b_ada, float* mod, int tid, int wave, int lane, int G) {
;     ...
;     for (int w = blockIdx.x; w < 256; w += G) {
;         const int cg0 = 144 * w, l = cg0 / MODW, n0 = cg0 % MODW;
;         if (lane < 36) {
;             const float* Wp = w_ada + (size_t)l * DM * MODW + (size_t)(wave * 256) * MODW + n0 + 4 * lane;
;             f32x4 a0 = {0.f, 0.f, 0.f, 0.f}, a1 = a0, a2 = a0, a3 = a0;
; #pragma unroll 8
;             for (int k = 0; k < 256; ++k) { const f32x4 wv = *(const f32x4*)(Wp + (size_t)k * MODW); const int kk = wave * 256 + k;
;                 a0 += wv * sl[kk]; a1 += wv * sl[DM + kk]; a2 += wv * sl[2 * DM + kk]; a3 += wv * sl[3 * DM + kk]; }
;             LAS float* r = red + (wave * 36 + lane) * 16;
;             *(LAS f32x4*)(r) = a0; *(LAS f32x4*)(r + 4) = a1; *(LAS f32x4*)(r + 8) = a2; *(LAS f32x4*)(r + 12) = a3;
.LBB0_25:
	v_lshl_add_u64 v[44:45], v[22:23], 0, s[40:41]
	v_add_co_u32_e32 v46, vcc, s3, v44
	global_load_dwordx4 v[28:31], v[44:45], off
	s_nop 0
	v_addc_co_u32_e32 v47, vcc, 0, v45, vcc
	v_add_co_u32_e32 v48, vcc, s12, v44
	v_addc_co_u32_e32 v49, vcc, 0, v45, vcc
	v_add_co_u32_e32 v60, vcc, s13, v44
	v_addc_co_u32_e32 v61, vcc, 0, v45, vcc
	v_add_co_u32_e32 v68, vcc, s14, v44
	v_addc_co_u32_e32 v69, vcc, 0, v45, vcc
	v_add_co_u32_e32 v72, vcc, s15, v44
	v_addc_co_u32_e32 v73, vcc, 0, v45, vcc
	v_add_co_u32_e32 v76, vcc, s16, v44
	s_add_u32 s40, s40, 0x90000
	s_nop 0
	v_addc_co_u32_e32 v77, vcc, 0, v45, vcc
	v_add_co_u32_e32 v80, vcc, s17, v44
	s_addc_u32 s41, s41, 0
	s_nop 0
	v_addc_co_u32_e32 v81, vcc, 0, v45, vcc
	global_load_dwordx4 v[44:47], v[46:47], off
	s_nop 0
	global_load_dwordx4 v[56:59], v[48:49], off
	global_load_dwordx4 v[64:67], v[60:61], off
	s_nop 0
	global_load_dwordx4 v[68:71], v[68:69], off
	s_nop 0
	global_load_dwordx4 v[72:75], v[72:73], off
	s_nop 0
	global_load_dwordx4 v[76:79], v[76:77], off
	s_nop 0
	global_load_dwordx4 v[80:83], v[80:81], off
	v_lshl_add_u64 v[160:161], v[22:23], 0, s[40:41]
	v_add_co_u32_e32 v162, vcc, s3, v160
	global_load_dwordx4 v[144:147], v[160:161], off
	s_nop 0
	v_addc_co_u32_e32 v163, vcc, 0, v161, vcc
	v_add_co_u32_e32 v164, vcc, s12, v160
	v_addc_co_u32_e32 v165, vcc, 0, v161, vcc
	v_add_co_u32_e32 v176, vcc, s13, v160
	v_addc_co_u32_e32 v177, vcc, 0, v161, vcc
	v_add_co_u32_e32 v184, vcc, s14, v160
	v_addc_co_u32_e32 v185, vcc, 0, v161, vcc
	v_add_co_u32_e32 v188, vcc, s15, v160
	v_addc_co_u32_e32 v189, vcc, 0, v161, vcc
	v_add_co_u32_e32 v192, vcc, s16, v160
	s_add_u32 s40, s40, 0x90000
	s_nop 0
	v_addc_co_u32_e32 v193, vcc, 0, v161, vcc
	v_add_co_u32_e32 v196, vcc, s17, v160
	s_addc_u32 s41, s41, 0
	s_nop 0
	v_addc_co_u32_e32 v197, vcc, 0, v161, vcc
	global_load_dwordx4 v[160:163], v[162:163], off
	s_nop 0
	global_load_dwordx4 v[172:175], v[164:165], off
	global_load_dwordx4 v[180:183], v[176:177], off
	s_nop 0
	global_load_dwordx4 v[184:187], v[184:185], off
	s_nop 0
	global_load_dwordx4 v[188:191], v[188:189], off
	s_nop 0
	global_load_dwordx4 v[192:195], v[192:193], off
	s_nop 0
	global_load_dwordx4 v[196:199], v[196:197], off
	v_mov_b32_e32 v51, s20
	s_nop 0
	ds_read_b128 v[32:35], v51
	ds_read_b128 v[36:39], v51 offset:16
	ds_read_b128 v[40:43], v51 offset:8192
	s_nop 0
	s_waitcnt lgkmcnt(0)
	v_mov_b32_e32 v54, v43
	ds_read_b128 v[84:87], v51 offset:8208
	ds_read_b128 v[88:91], v51 offset:16384
	ds_read_b128 v[92:95], v51 offset:16400
	ds_read_b128 v[96:99], v51 offset:24576
	ds_read_b128 v[100:103], v51 offset:24592
	v_mov_b32_e32 v48, v35
	s_waitcnt lgkmcnt(3)
	v_mov_b32_e32 v60, v91
	s_add_i32 s20, s20, 32
	s_waitcnt lgkmcnt(1)
	v_mov_b32_e32 v62, v99
	v_mov_b32_e32 v104, v39
	v_mov_b32_e32 v106, v87
	v_mov_b32_e32 v108, v95
	s_waitcnt lgkmcnt(0)
	v_mov_b32_e32 v110, v103
	s_waitcnt vmcnt(15)
	v_pk_fma_f32 v[4:5], v[30:31], v[32:33], v[4:5] op_sel_hi:[1,0,1]
	v_pk_fma_f32 v[2:3], v[28:29], v[32:33], v[2:3] op_sel_hi:[1,0,1]
	v_pk_fma_f32 v[8:9], v[30:31], v[40:41], v[8:9] op_sel_hi:[1,0,1]
	v_pk_fma_f32 v[6:7], v[28:29], v[40:41], v[6:7] op_sel_hi:[1,0,1]
	v_pk_fma_f32 v[16:17], v[30:31], v[88:89], v[16:17] op_sel_hi:[1,0,1]
	v_pk_fma_f32 v[14:15], v[28:29], v[88:89], v[14:15] op_sel_hi:[1,0,1]
	v_pk_fma_f32 v[12:13], v[30:31], v[96:97], v[12:13] op_sel_hi:[1,0,1]
	v_pk_fma_f32 v[10:11], v[28:29], v[96:97], v[10:11] op_sel_hi:[1,0,1]
	s_waitcnt vmcnt(14)
	v_pk_fma_f32 v[2:3], v[44:45], v[32:33], v[2:3] op_sel:[0,1,0]
	v_pk_fma_f32 v[4:5], v[46:47], v[32:33], v[4:5] op_sel:[0,1,0]
	v_pk_fma_f32 v[6:7], v[44:45], v[40:41], v[6:7] op_sel:[0,1,0]
	v_pk_fma_f32 v[8:9], v[46:47], v[40:41], v[8:9] op_sel:[0,1,0]
	v_pk_fma_f32 v[14:15], v[44:45], v[88:89], v[14:15] op_sel:[0,1,0]
	v_pk_fma_f32 v[16:17], v[46:47], v[88:89], v[16:17] op_sel:[0,1,0]
	v_pk_fma_f32 v[10:11], v[44:45], v[96:97], v[10:11] op_sel:[0,1,0]
	v_pk_fma_f32 v[12:13], v[46:47], v[96:97], v[12:13] op_sel:[0,1,0]
	s_waitcnt vmcnt(13)
	v_pk_fma_f32 v[4:5], v[58:59], v[34:35], v[4:5] op_sel_hi:[1,0,1]
	v_pk_fma_f32 v[2:3], v[56:57], v[34:35], v[2:3] op_sel_hi:[1,0,1]
	v_pk_fma_f32 v[8:9], v[58:59], v[42:43], v[8:9] op_sel_hi:[1,0,1]
	v_pk_fma_f32 v[6:7], v[56:57], v[42:43], v[6:7] op_sel_hi:[1,0,1]
	v_pk_fma_f32 v[16:17], v[58:59], v[90:91], v[16:17] op_sel_hi:[1,0,1]
	v_pk_fma_f32 v[14:15], v[56:57], v[90:91], v[14:15] op_sel_hi:[1,0,1]
	v_pk_fma_f32 v[12:13], v[58:59], v[98:99], v[12:13] op_sel_hi:[1,0,1]
	v_pk_fma_f32 v[10:11], v[56:57], v[98:99], v[10:11] op_sel_hi:[1,0,1]
	s_waitcnt vmcnt(12)
	v_pk_fma_f32 v[4:5], v[66:67], v[48:49], v[4:5] op_sel_hi:[1,0,1]
	v_pk_fma_f32 v[2:3], v[64:65], v[48:49], v[2:3] op_sel_hi:[1,0,1]
	v_pk_fma_f32 v[8:9], v[66:67], v[54:55], v[8:9] op_sel_hi:[1,0,1]
	v_pk_fma_f32 v[6:7], v[64:65], v[54:55], v[6:7] op_sel_hi:[1,0,1]
	v_pk_fma_f32 v[16:17], v[66:67], v[60:61], v[16:17] op_sel_hi:[1,0,1]
	v_pk_fma_f32 v[14:15], v[64:65], v[60:61], v[14:15] op_sel_hi:[1,0,1]
	v_pk_fma_f32 v[12:13], v[66:67], v[62:63], v[12:13] op_sel_hi:[1,0,1]
	v_pk_fma_f32 v[10:11], v[64:65], v[62:63], v[10:11] op_sel_hi:[1,0,1]
	s_waitcnt vmcnt(11)
	v_pk_fma_f32 v[4:5], v[70:71], v[36:37], v[4:5] op_sel_hi:[1,0,1]
	v_pk_fma_f32 v[2:3], v[68:69], v[36:37], v[2:3] op_sel_hi:[1,0,1]
	v_pk_fma_f32 v[8:9], v[70:71], v[84:85], v[8:9] op_sel_hi:[1,0,1]
	v_pk_fma_f32 v[6:7], v[68:69], v[84:85], v[6:7] op_sel_hi:[1,0,1]
	v_pk_fma_f32 v[16:17], v[70:71], v[92:93], v[16:17] op_sel_hi:[1,0,1]
	v_pk_fma_f32 v[14:15], v[68:69], v[92:93], v[14:15] op_sel_hi:[1,0,1]
	v_pk_fma_f32 v[12:13], v[70:71], v[100:101], v[12:13] op_sel_hi:[1,0,1]
	v_pk_fma_f32 v[10:11], v[68:69], v[100:101], v[10:11] op_sel_hi:[1,0,1]
	s_waitcnt vmcnt(10)
; __device__ __forceinline__ void p0_mod(LAS unsigned char* lds, const float* c, const float* w_ada, const float* b_ada, float* mod, int tid, int wave, int lane, int G) {
;     ...
;             for (int k = 0; k < 256; ++k) { const f32x4 wv = *(const f32x4*)(Wp + (size_t)k * MODW); const int kk = wave * 256 + k;
;                 a0 += wv * sl[kk]; a1 += wv * sl[DM + kk]; a2 += wv * sl[2 * DM + kk]; a3 += wv * sl[3 * DM + kk]; }
	v_pk_fma_f32 v[4:5], v[74:75], v[36:37], v[4:5] op_sel:[0,1,0]
	v_pk_fma_f32 v[2:3], v[72:73], v[36:37], v[2:3] op_sel:[0,1,0]
	v_pk_fma_f32 v[8:9], v[74:75], v[84:85], v[8:9] op_sel:[0,1,0]
	v_pk_fma_f32 v[6:7], v[72:73], v[84:85], v[6:7] op_sel:[0,1,0]
	v_pk_fma_f32 v[16:17], v[74:75], v[92:93], v[16:17] op_sel:[0,1,0]
	v_pk_fma_f32 v[14:15], v[72:73], v[92:93], v[14:15] op_sel:[0,1,0]
	v_pk_fma_f32 v[12:13], v[74:75], v[100:101], v[12:13] op_sel:[0,1,0]
	v_pk_fma_f32 v[10:11], v[72:73], v[100:101], v[10:11] op_sel:[0,1,0]
	s_waitcnt vmcnt(9)
	v_pk_fma_f32 v[4:5], v[78:79], v[38:39], v[4:5] op_sel_hi:[1,0,1]
	v_pk_fma_f32 v[2:3], v[76:77], v[38:39], v[2:3] op_sel_hi:[1,0,1]
	v_pk_fma_f32 v[8:9], v[78:79], v[86:87], v[8:9] op_sel_hi:[1,0,1]
	v_pk_fma_f32 v[6:7], v[76:77], v[86:87], v[6:7] op_sel_hi:[1,0,1]
	v_pk_fma_f32 v[16:17], v[78:79], v[94:95], v[16:17] op_sel_hi:[1,0,1]
	v_pk_fma_f32 v[14:15], v[76:77], v[94:95], v[14:15] op_sel_hi:[1,0,1]
	v_pk_fma_f32 v[12:13], v[78:79], v[102:103], v[12:13] op_sel_hi:[1,0,1]
	v_pk_fma_f32 v[10:11], v[76:77], v[102:103], v[10:11] op_sel_hi:[1,0,1]
	s_waitcnt vmcnt(8)
	v_pk_fma_f32 v[4:5], v[82:83], v[104:105], v[4:5] op_sel_hi:[1,0,1]
	v_pk_fma_f32 v[2:3], v[80:81], v[104:105], v[2:3] op_sel_hi:[1,0,1]
	v_pk_fma_f32 v[8:9], v[82:83], v[106:107], v[8:9] op_sel_hi:[1,0,1]
	v_pk_fma_f32 v[6:7], v[80:81], v[106:107], v[6:7] op_sel_hi:[1,0,1]
	v_pk_fma_f32 v[16:17], v[82:83], v[108:109], v[16:17] op_sel_hi:[1,0,1]
	v_pk_fma_f32 v[14:15], v[80:81], v[108:109], v[14:15] op_sel_hi:[1,0,1]
	v_pk_fma_f32 v[12:13], v[82:83], v[110:111], v[12:13] op_sel_hi:[1,0,1]
	v_pk_fma_f32 v[10:11], v[80:81], v[110:111], v[10:11] op_sel_hi:[1,0,1]
	v_mov_b32_e32 v51, s20
	s_nop 0
	ds_read_b128 v[32:35], v51
	ds_read_b128 v[36:39], v51 offset:16
	ds_read_b128 v[40:43], v51 offset:8192
	s_nop 0
	s_waitcnt lgkmcnt(0)
	v_mov_b32_e32 v54, v43
	ds_read_b128 v[84:87], v51 offset:8208
	ds_read_b128 v[88:91], v51 offset:16384
	ds_read_b128 v[92:95], v51 offset:16400
	ds_read_b128 v[96:99], v51 offset:24576
	ds_read_b128 v[100:103], v51 offset:24592
	v_mov_b32_e32 v48, v35
	s_waitcnt lgkmcnt(3)
	v_mov_b32_e32 v60, v91
	s_add_i32 s20, s20, 32
	s_waitcnt lgkmcnt(1)
	v_mov_b32_e32 v62, v99
	v_mov_b32_e32 v104, v39
	v_mov_b32_e32 v106, v87
	v_mov_b32_e32 v108, v95
	s_waitcnt lgkmcnt(0)
	v_mov_b32_e32 v110, v103
	s_cmp_eq_u32 s40, 0x1200000
	s_waitcnt vmcnt(7)
	v_pk_fma_f32 v[4:5], v[146:147], v[32:33], v[4:5] op_sel_hi:[1,0,1]
	v_pk_fma_f32 v[2:3], v[144:145], v[32:33], v[2:3] op_sel_hi:[1,0,1]
	v_pk_fma_f32 v[8:9], v[146:147], v[40:41], v[8:9] op_sel_hi:[1,0,1]
	v_pk_fma_f32 v[6:7], v[144:145], v[40:41], v[6:7] op_sel_hi:[1,0,1]
	v_pk_fma_f32 v[16:17], v[146:147], v[88:89], v[16:17] op_sel_hi:[1,0,1]
	v_pk_fma_f32 v[14:15], v[144:145], v[88:89], v[14:15] op_sel_hi:[1,0,1]
	v_pk_fma_f32 v[12:13], v[146:147], v[96:97], v[12:13] op_sel_hi:[1,0,1]
	v_pk_fma_f32 v[10:11], v[144:145], v[96:97], v[10:11] op_sel_hi:[1,0,1]
	s_waitcnt vmcnt(6)
	v_pk_fma_f32 v[2:3], v[160:161], v[32:33], v[2:3] op_sel:[0,1,0]
	v_pk_fma_f32 v[4:5], v[162:163], v[32:33], v[4:5] op_sel:[0,1,0]
	v_pk_fma_f32 v[6:7], v[160:161], v[40:41], v[6:7] op_sel:[0,1,0]
	v_pk_fma_f32 v[8:9], v[162:163], v[40:41], v[8:9] op_sel:[0,1,0]
	v_pk_fma_f32 v[14:15], v[160:161], v[88:89], v[14:15] op_sel:[0,1,0]
	v_pk_fma_f32 v[16:17], v[162:163], v[88:89], v[16:17] op_sel:[0,1,0]
	v_pk_fma_f32 v[10:11], v[160:161], v[96:97], v[10:11] op_sel:[0,1,0]
	v_pk_fma_f32 v[12:13], v[162:163], v[96:97], v[12:13] op_sel:[0,1,0]
	s_waitcnt vmcnt(5)
; #define LAS __attribute__((address_space(3)))
; __device__ __forceinline__ void p0_mod(LAS unsigned char* lds, const float* c, const float* w_ada, const float* b_ada, float* mod, int tid, int wave, int lane, int G) {
;     ...
;             for (int k = 0; k < 256; ++k) { const f32x4 wv = *(const f32x4*)(Wp + (size_t)k * MODW); const int kk = wave * 256 + k;
;                 a0 += wv * sl[kk]; a1 += wv * sl[DM + kk]; a2 += wv * sl[2 * DM + kk]; a3 += wv * sl[3 * DM + kk]; }
;             LAS float* r = red + (wave * 36 + lane) * 16;
;             *(LAS f32x4*)(r) = a0; *(LAS f32x4*)(r + 4) = a1; *(LAS f32x4*)(r + 8) = a2; *(LAS f32x4*)(r + 12) = a3;
	v_pk_fma_f32 v[4:5], v[174:175], v[34:35], v[4:5] op_sel_hi:[1,0,1]
	v_pk_fma_f32 v[2:3], v[172:173], v[34:35], v[2:3] op_sel_hi:[1,0,1]
	v_pk_fma_f32 v[8:9], v[174:175], v[42:43], v[8:9] op_sel_hi:[1,0,1]
	v_pk_fma_f32 v[6:7], v[172:173], v[42:43], v[6:7] op_sel_hi:[1,0,1]
	v_pk_fma_f32 v[16:17], v[174:175], v[90:91], v[16:17] op_sel_hi:[1,0,1]
	v_pk_fma_f32 v[14:15], v[172:173], v[90:91], v[14:15] op_sel_hi:[1,0,1]
	v_pk_fma_f32 v[12:13], v[174:175], v[98:99], v[12:13] op_sel_hi:[1,0,1]
	v_pk_fma_f32 v[10:11], v[172:173], v[98:99], v[10:11] op_sel_hi:[1,0,1]
	s_waitcnt vmcnt(4)
	v_pk_fma_f32 v[4:5], v[182:183], v[48:49], v[4:5] op_sel_hi:[1,0,1]
	v_pk_fma_f32 v[2:3], v[180:181], v[48:49], v[2:3] op_sel_hi:[1,0,1]
	v_pk_fma_f32 v[8:9], v[182:183], v[54:55], v[8:9] op_sel_hi:[1,0,1]
	v_pk_fma_f32 v[6:7], v[180:181], v[54:55], v[6:7] op_sel_hi:[1,0,1]
	v_pk_fma_f32 v[16:17], v[182:183], v[60:61], v[16:17] op_sel_hi:[1,0,1]
	v_pk_fma_f32 v[14:15], v[180:181], v[60:61], v[14:15] op_sel_hi:[1,0,1]
	v_pk_fma_f32 v[12:13], v[182:183], v[62:63], v[12:13] op_sel_hi:[1,0,1]
	v_pk_fma_f32 v[10:11], v[180:181], v[62:63], v[10:11] op_sel_hi:[1,0,1]
	s_waitcnt vmcnt(3)
	v_pk_fma_f32 v[4:5], v[186:187], v[36:37], v[4:5] op_sel_hi:[1,0,1]
	v_pk_fma_f32 v[2:3], v[184:185], v[36:37], v[2:3] op_sel_hi:[1,0,1]
	v_pk_fma_f32 v[8:9], v[186:187], v[84:85], v[8:9] op_sel_hi:[1,0,1]
	v_pk_fma_f32 v[6:7], v[184:185], v[84:85], v[6:7] op_sel_hi:[1,0,1]
	v_pk_fma_f32 v[16:17], v[186:187], v[92:93], v[16:17] op_sel_hi:[1,0,1]
	v_pk_fma_f32 v[14:15], v[184:185], v[92:93], v[14:15] op_sel_hi:[1,0,1]
	v_pk_fma_f32 v[12:13], v[186:187], v[100:101], v[12:13] op_sel_hi:[1,0,1]
	v_pk_fma_f32 v[10:11], v[184:185], v[100:101], v[10:11] op_sel_hi:[1,0,1]
	s_waitcnt vmcnt(2)
	v_pk_fma_f32 v[4:5], v[190:191], v[36:37], v[4:5] op_sel:[0,1,0]
	v_pk_fma_f32 v[2:3], v[188:189], v[36:37], v[2:3] op_sel:[0,1,0]
	v_pk_fma_f32 v[8:9], v[190:191], v[84:85], v[8:9] op_sel:[0,1,0]
	v_pk_fma_f32 v[6:7], v[188:189], v[84:85], v[6:7] op_sel:[0,1,0]
	v_pk_fma_f32 v[16:17], v[190:191], v[92:93], v[16:17] op_sel:[0,1,0]
	v_pk_fma_f32 v[14:15], v[188:189], v[92:93], v[14:15] op_sel:[0,1,0]
	v_pk_fma_f32 v[12:13], v[190:191], v[100:101], v[12:13] op_sel:[0,1,0]
	v_pk_fma_f32 v[10:11], v[188:189], v[100:101], v[10:11] op_sel:[0,1,0]
	s_waitcnt vmcnt(1)
	v_pk_fma_f32 v[4:5], v[194:195], v[38:39], v[4:5] op_sel_hi:[1,0,1]
	v_pk_fma_f32 v[2:3], v[192:193], v[38:39], v[2:3] op_sel_hi:[1,0,1]
	v_pk_fma_f32 v[8:9], v[194:195], v[86:87], v[8:9] op_sel_hi:[1,0,1]
	v_pk_fma_f32 v[6:7], v[192:193], v[86:87], v[6:7] op_sel_hi:[1,0,1]
	v_pk_fma_f32 v[16:17], v[194:195], v[94:95], v[16:17] op_sel_hi:[1,0,1]
	v_pk_fma_f32 v[14:15], v[192:193], v[94:95], v[14:15] op_sel_hi:[1,0,1]
	v_pk_fma_f32 v[12:13], v[194:195], v[102:103], v[12:13] op_sel_hi:[1,0,1]
	v_pk_fma_f32 v[10:11], v[192:193], v[102:103], v[10:11] op_sel_hi:[1,0,1]
	s_waitcnt vmcnt(0)
	v_pk_fma_f32 v[4:5], v[198:199], v[104:105], v[4:5] op_sel_hi:[1,0,1]
	v_pk_fma_f32 v[2:3], v[196:197], v[104:105], v[2:3] op_sel_hi:[1,0,1]
	v_pk_fma_f32 v[8:9], v[198:199], v[106:107], v[8:9] op_sel_hi:[1,0,1]
	v_pk_fma_f32 v[6:7], v[196:197], v[106:107], v[6:7] op_sel_hi:[1,0,1]
	v_pk_fma_f32 v[16:17], v[198:199], v[108:109], v[16:17] op_sel_hi:[1,0,1]
	v_pk_fma_f32 v[14:15], v[196:197], v[108:109], v[14:15] op_sel_hi:[1,0,1]
	v_pk_fma_f32 v[12:13], v[198:199], v[110:111], v[12:13] op_sel_hi:[1,0,1]
	v_pk_fma_f32 v[10:11], v[196:197], v[110:111], v[10:11] op_sel_hi:[1,0,1]
	s_cbranch_scc0 .LBB0_25
	ds_write_b128 v24, v[2:5] offset:32768
	ds_write_b128 v24, v[6:9] offset:32784
	ds_write_b128 v24, v[14:17] offset:32800
	ds_write_b128 v24, v[10:13] offset:32816
